# adds: final RMSNorm loop prefetches the next row and no longer waits for the previous row's stores (counted vmcnt)
# baseline (speedup 1.0000x reference)
; __device__ __forceinline__ float rstd_of(float ss, float invn) { return __builtin_amdgcn_rsqf(ss * invn + EPS); }
; __global__ void __launch_bounds__(NTHREADS, 2) fwd_megakernel(Params Pkern) {
;     ...
;     if (PH_ON && PM(11)) {
;         SETUP
;         const float* rsf = RS + (size_t)8 * T; const float* fw = Pp->final_norm;
;         f32x4 w[4];
; #pragma unroll
;         for (int j = 0; j < 4; ++j) w[j] = *((const f32x4*)fw + lane + 64 * j);
;         for (int m = gw; m < T; m += NGW) {
;             const float t = rstd_of(rsf[m], 1.f / 1024.f); f32x4* orow = (f32x4*)(OUT + (size_t)m * DM) + lane;
.LBB0_1436:
	s_cmp_lt_i32 s94, 22
	s_cselect_b64 s[0:1], -1, 0
	s_cmp_gt_i32 s95, 21
	s_cselect_b64 s[2:3], -1, 0
	s_and_b64 s[0:1], s[0:1], s[2:3]
	s_and_b64 vcc, exec, s[0:1]
	s_cbranch_vccz .LBB0_1440
	s_mov_b32 s0, 0x8000
	v_ashrrev_i32_e32 v0, 6, v234
	v_add_u32_e32 v16, s93, v0
	v_cmp_gt_i32_e32 vcc, s0, v16
	s_and_saveexec_b64 s[0:1], vcc
	s_cbranch_execz .LBB0_1440
	s_load_dwordx4 s[0:3], s[90:91], 0xc0
	s_load_dwordx2 s[4:5], s[90:91], 0xd0
	v_lshlrev_b32_e32 v0, 4, v234
	v_and_b32_e32 v22, 0x3f0, v0
	v_ashrrev_i32_e32 v17, 31, v16
	s_waitcnt lgkmcnt(0)
	global_load_dwordx4 v[0:3], v22, s[0:1]
	global_load_dwordx4 v[4:7], v22, s[0:1] offset:1024
	global_load_dwordx4 v[8:11], v22, s[0:1] offset:2048
	global_load_dwordx4 v[12:15], v22, s[0:1] offset:3072
	v_lshlrev_b64 v[20:21], 12, v[16:17]
	v_or_b32_e32 v20, v20, v22
	v_lshl_add_u64 v[18:19], v[16:17], 2, s[4:5]
	s_mov_b64 s[0:1], 0x100000
	v_lshl_add_u64 v[20:21], s[2:3], 0, v[20:21]
	s_mov_b64 s[2:3], 0x800
	v_lshl_add_u64 v[18:19], v[18:19], 0, s[0:1]
	s_lshl_b64 s[0:1], s[26:27], 2
	v_lshl_add_u64 v[20:21], v[20:21], 0, s[2:3]
	s_lshl_b64 s[2:3], s[26:27], 12
	s_mov_b64 s[4:5], 0
	v_mov_b32_e32 v17, 0x358637bd
	s_movk_i32 s6, 0x7fff
	v_readfirstlane_b32 s7, v16
	s_mov_b32 s8, 0
	global_load_dword v38, v[18:19], off
	global_load_dwordx4 v[22:25], v[20:21], off offset:-2048
	global_load_dwordx4 v[26:29], v[20:21], off offset:-1024
	global_load_dwordx4 v[30:33], v[20:21], off
	global_load_dwordx4 v[34:37], v[20:21], off offset:1024
.Lfin_loop:
	s_add_i32 s7, s7, s26
	s_cmp_gt_i32 s7, s6
	s_cbranch_scc1 .Lfin_lastA
	v_lshl_add_u64 v[60:61], v[18:19], 0, s[0:1]
	v_lshl_add_u64 v[62:63], v[20:21], 0, s[2:3]
	global_load_dword v56, v[60:61], off
	global_load_dwordx4 v[40:43], v[62:63], off offset:-2048
	global_load_dwordx4 v[44:47], v[62:63], off offset:-1024
	global_load_dwordx4 v[48:51], v[62:63], off
	global_load_dwordx4 v[52:55], v[62:63], off offset:1024
	s_cmp_eq_u32 s8, 0
	s_cbranch_scc1 .Lfin_firstA
	s_waitcnt vmcnt(9)
	s_branch .Lfin_compA
.Lfin_firstA:
	s_mov_b32 s8, 1
	s_waitcnt vmcnt(5)
	s_branch .Lfin_compA

; __device__ __forceinline__ float rstd_of(float ss, float invn) { return __builtin_amdgcn_rsqf(ss * invn + EPS); }
; __global__ void __launch_bounds__(NTHREADS, 2) fwd_megakernel(Params Pkern) {
;     ...
;         for (int m = gw; m < T; m += NGW) {
;             const float t = rstd_of(rsf[m], 1.f / 1024.f); f32x4* orow = (f32x4*)(OUT + (size_t)m * DM) + lane;
; #pragma unroll
;             for (int j = 0; j < 4; ++j) orow[64 * j] = orow[64 * j] * t * w[j];
;         }
.Lfin_compA:
	v_fmamk_f32 v38, v38, 0x3a800000, v17
	v_rsq_f32_e32 v38, v38
	s_nop 0
	v_pk_mul_f32 v[22:23], v[38:39], v[22:23] op_sel_hi:[0,1]
	v_pk_mul_f32 v[24:25], v[38:39], v[24:25] op_sel_hi:[0,1]
	v_pk_mul_f32 v[26:27], v[38:39], v[26:27] op_sel_hi:[0,1]
	v_pk_mul_f32 v[28:29], v[38:39], v[28:29] op_sel_hi:[0,1]
	v_pk_mul_f32 v[30:31], v[38:39], v[30:31] op_sel_hi:[0,1]
	v_pk_mul_f32 v[32:33], v[38:39], v[32:33] op_sel_hi:[0,1]
	v_pk_mul_f32 v[34:35], v[38:39], v[34:35] op_sel_hi:[0,1]
	v_pk_mul_f32 v[36:37], v[38:39], v[36:37] op_sel_hi:[0,1]
	v_pk_mul_f32 v[22:23], v[0:1], v[22:23]
	v_pk_mul_f32 v[24:25], v[2:3], v[24:25]
	v_pk_mul_f32 v[26:27], v[4:5], v[26:27]
	v_pk_mul_f32 v[28:29], v[6:7], v[28:29]
	v_pk_mul_f32 v[30:31], v[8:9], v[30:31]
	v_pk_mul_f32 v[32:33], v[10:11], v[32:33]
	v_pk_mul_f32 v[34:35], v[12:13], v[34:35]
	v_pk_mul_f32 v[36:37], v[14:15], v[36:37]
	global_store_dwordx4 v[20:21], v[22:25], off offset:-2048
	global_store_dwordx4 v[20:21], v[26:29], off offset:-1024
	global_store_dwordx4 v[20:21], v[30:33], off
	global_store_dwordx4 v[20:21], v[34:37], off offset:1024
	s_cmp_gt_i32 s7, s6
	s_cbranch_scc1 .Lfin_done
	s_add_i32 s7, s7, s26
	v_lshl_add_u64 v[18:19], v[60:61], 0, s[0:1]
	v_lshl_add_u64 v[20:21], v[62:63], 0, s[2:3]
	s_cmp_gt_i32 s7, s6
	s_cbranch_scc1 .Lfin_lastB
	global_load_dword v38, v[18:19], off
	global_load_dwordx4 v[22:25], v[20:21], off offset:-2048
	global_load_dwordx4 v[26:29], v[20:21], off offset:-1024
	global_load_dwordx4 v[30:33], v[20:21], off
	global_load_dwordx4 v[34:37], v[20:21], off offset:1024
	s_waitcnt vmcnt(9)
	s_branch .Lfin_compB
